# out-proj and FFN-down epilogues: residual loads issued together before the barrier, counted vmcnt waits instead of one load-wait-store round trip per 16 bytes
# speedup vs baseline: 1.0235x; 1.0235x over previous
; template <int MODE, bool BIG = false> DI void gemm_tile(const Params& p, int tm, int tn, int kv, char* smem) {
;     ...
;   const int row = tid >> 1, half = tid & 1;
;   float* crow = Cs + row * 132 + half * 64;
;   const float4* crow4 = (const float4*)crow;
;   const int m = tm * RB + hh * 128 + row;
;   const int col0 = tn * 128 + half * 64;
;     ...
;   } else if constexpr (MODE == G_OUT) {
;     const float4* x4 = (const float4*)(p.x + (size_t)m * 1024 + col0);
;     float4* o4 = (float4*)(p.out + (size_t)m * 1024 + col0);
; #pragma unroll
;     for (int c4 = 0; c4 < 16; ++c4) { float4 v = crow4[c4], xx = x4[c4]; o4[c4] = make_float4(v.x + xx.x, v.y + xx.y, v.z + xx.z, v.w + xx.w); }
.LBB0_940:
	s_or_b64 exec, exec, s[6:7]
	v_lshl_add_u32 v136, s14, 7, v134
	v_ashrrev_i32_e32 v137, 31, v136
	v_lshlrev_b64 v[148:149], 12, v[136:137]
	v_lshl_add_u64 v[150:151], v[128:129], 0, v[148:149]
	global_load_dwordx4 v[184:187], v[150:151], off
	global_load_dwordx4 v[192:195], v[150:151], off offset:16
	global_load_dwordx4 v[200:203], v[150:151], off offset:32
	global_load_dwordx4 v[208:211], v[150:151], off offset:48
	global_load_dwordx4 v[216:219], v[150:151], off offset:64
	global_load_dwordx4 v[224:227], v[150:151], off offset:80
	global_load_dwordx4 v[188:191], v[150:151], off offset:96
	global_load_dwordx4 v[196:199], v[150:151], off offset:112
	global_load_dwordx4 v[204:207], v[150:151], off offset:128
	global_load_dwordx4 v[212:215], v[150:151], off offset:144
	global_load_dwordx4 v[220:223], v[150:151], off offset:160
	global_load_dwordx4 v[228:231], v[150:151], off offset:176
	global_load_dwordx4 v[136:139], v[150:151], off offset:192
	s_waitcnt lgkmcnt(0)
	s_barrier
	v_lshl_add_u64 v[148:149], v[130:131], 0, v[148:149]
	s_xor_b64 s[2:3], s[2:3], -1
	s_mov_b32 s14, 1
	s_andn2_b64 vcc, exec, s[2:3]
	s_mov_b64 s[2:3], 0
	ds_read_b128 v[140:143], v133
	ds_read_b128 v[144:147], v133 offset:16
	s_waitcnt vmcnt(12) lgkmcnt(1)
	v_pk_add_f32 v[184:185], v[140:141], v[184:185]
	v_pk_add_f32 v[186:187], v[142:143], v[186:187]
	global_store_dwordx4 v[148:149], v[184:187], off
	s_waitcnt vmcnt(12) lgkmcnt(0)
	v_pk_add_f32 v[192:193], v[144:145], v[192:193]
	v_pk_add_f32 v[194:195], v[146:147], v[194:195]
	global_store_dwordx4 v[148:149], v[192:195], off offset:16
	global_load_dwordx4 v[184:187], v[150:151], off offset:208
	ds_read_b128 v[140:143], v133 offset:32
	ds_read_b128 v[144:147], v133 offset:48
	s_waitcnt vmcnt(13) lgkmcnt(1)
	v_pk_add_f32 v[200:201], v[140:141], v[200:201]
	v_pk_add_f32 v[202:203], v[142:143], v[202:203]
	global_store_dwordx4 v[148:149], v[200:203], off offset:32
	global_load_dwordx4 v[192:195], v[150:151], off offset:224
	s_waitcnt vmcnt(14) lgkmcnt(0)
	v_pk_add_f32 v[208:209], v[144:145], v[208:209]
	v_pk_add_f32 v[210:211], v[146:147], v[210:211]
	global_store_dwordx4 v[148:149], v[208:211], off offset:48
	global_load_dwordx4 v[200:203], v[150:151], off offset:240
	ds_read_b128 v[140:143], v133 offset:64
	ds_read_b128 v[144:147], v133 offset:80
	s_waitcnt vmcnt(15) lgkmcnt(1)
	v_pk_add_f32 v[216:217], v[140:141], v[216:217]
	v_pk_add_f32 v[218:219], v[142:143], v[218:219]
	global_store_dwordx4 v[148:149], v[216:219], off offset:64
	s_waitcnt vmcnt(15) lgkmcnt(0)
	v_pk_add_f32 v[224:225], v[144:145], v[224:225]
	v_pk_add_f32 v[226:227], v[146:147], v[226:227]
	global_store_dwordx4 v[148:149], v[224:227], off offset:80
	ds_read_b128 v[140:143], v133 offset:96
	ds_read_b128 v[144:147], v133 offset:112
	s_waitcnt vmcnt(15) lgkmcnt(1)
	v_pk_add_f32 v[188:189], v[140:141], v[188:189]
	v_pk_add_f32 v[190:191], v[142:143], v[190:191]
	global_store_dwordx4 v[148:149], v[188:191], off offset:96
	s_waitcnt vmcnt(15) lgkmcnt(0)
	v_pk_add_f32 v[196:197], v[144:145], v[196:197]
	v_pk_add_f32 v[198:199], v[146:147], v[198:199]
	global_store_dwordx4 v[148:149], v[196:199], off offset:112
	ds_read_b128 v[140:143], v133 offset:128
	ds_read_b128 v[144:147], v133 offset:144
	s_waitcnt vmcnt(15) lgkmcnt(1)
	v_pk_add_f32 v[204:205], v[140:141], v[204:205]
	v_pk_add_f32 v[206:207], v[142:143], v[206:207]
	global_store_dwordx4 v[148:149], v[204:207], off offset:128
	s_waitcnt vmcnt(15) lgkmcnt(0)
	v_pk_add_f32 v[212:213], v[144:145], v[212:213]
	v_pk_add_f32 v[214:215], v[146:147], v[214:215]
	global_store_dwordx4 v[148:149], v[212:215], off offset:144
	ds_read_b128 v[140:143], v133 offset:160
	ds_read_b128 v[144:147], v133 offset:176
	s_waitcnt vmcnt(15) lgkmcnt(1)
	v_pk_add_f32 v[220:221], v[140:141], v[220:221]
	v_pk_add_f32 v[222:223], v[142:143], v[222:223]
	global_store_dwordx4 v[148:149], v[220:223], off offset:160
	s_waitcnt vmcnt(15) lgkmcnt(0)
	v_pk_add_f32 v[228:229], v[144:145], v[228:229]
	v_pk_add_f32 v[230:231], v[146:147], v[230:231]
	global_store_dwordx4 v[148:149], v[228:231], off offset:176
	ds_read_b128 v[140:143], v133 offset:192
	ds_read_b128 v[144:147], v133 offset:208
	s_waitcnt vmcnt(15) lgkmcnt(1)
	v_pk_add_f32 v[136:137], v[140:141], v[136:137]
	v_pk_add_f32 v[138:139], v[142:143], v[138:139]
	global_store_dwordx4 v[148:149], v[136:139], off offset:192
	s_waitcnt vmcnt(13) lgkmcnt(0)
	v_pk_add_f32 v[184:185], v[144:145], v[184:185]
	v_pk_add_f32 v[186:187], v[146:147], v[186:187]
	global_store_dwordx4 v[148:149], v[184:187], off offset:208
	ds_read_b128 v[140:143], v133 offset:224
	ds_read_b128 v[144:147], v133 offset:240
	s_waitcnt vmcnt(12) lgkmcnt(1)
	v_pk_add_f32 v[192:193], v[140:141], v[192:193]
	v_pk_add_f32 v[194:195], v[142:143], v[194:195]
	global_store_dwordx4 v[148:149], v[192:195], off offset:224
	s_waitcnt vmcnt(11) lgkmcnt(0)
	v_pk_add_f32 v[200:201], v[144:145], v[200:201]
	v_pk_add_f32 v[202:203], v[146:147], v[202:203]
	global_store_dwordx4 v[148:149], v[200:203], off offset:240
	s_cbranch_vccz .LBB0_936

; template <int MODE, bool BIG = false> DI void gemm_tile(const Params& p, int tm, int tn, int kv, char* smem) {
;     ...
;   const int row = tid >> 1, half = tid & 1;
;   float* crow = Cs + row * 132 + half * 64;
;   const float4* crow4 = (const float4*)crow;
;   const int m = tm * RB + hh * 128 + row;
;   const int col0 = tn * 128 + half * 64;
;     ...
;   } else if constexpr (MODE == G_FF2) {
;     float4* o4 = (float4*)(p.out + (size_t)m * 1024 + col0);
; #pragma unroll
;     for (int c4 = 0; c4 < 16; ++c4) { float4 v = crow4[c4], xx = o4[c4]; o4[c4] = make_float4(v.x + xx.x, v.y + xx.y, v.z + xx.z, v.w + xx.w); }
.LBB0_1003:
	s_or_b64 exec, exec, s[4:5]
	v_lshl_add_u32 v130, s14, 7, v134
	v_ashrrev_i32_e32 v131, 31, v130
	v_lshlrev_b64 v[130:131], 12, v[130:131]
	v_lshl_add_u64 v[130:131], v[128:129], 0, v[130:131]
	global_load_dwordx4 v[188:191], v[130:131], off
	global_load_dwordx4 v[196:199], v[130:131], off offset:16
	global_load_dwordx4 v[204:207], v[130:131], off offset:32
	global_load_dwordx4 v[212:215], v[130:131], off offset:48
	global_load_dwordx4 v[220:223], v[130:131], off offset:64
	global_load_dwordx4 v[228:231], v[130:131], off offset:80
	global_load_dwordx4 v[192:195], v[130:131], off offset:96
	global_load_dwordx4 v[200:203], v[130:131], off offset:112
	global_load_dwordx4 v[208:211], v[130:131], off offset:128
	global_load_dwordx4 v[216:219], v[130:131], off offset:144
	global_load_dwordx4 v[224:227], v[130:131], off offset:160
	global_load_dwordx4 v[232:235], v[130:131], off offset:176
	global_load_dwordx4 v[144:147], v[130:131], off offset:192
	global_load_dwordx4 v[148:151], v[130:131], off offset:208
	s_waitcnt lgkmcnt(0)
	s_barrier
	s_xor_b64 s[4:5], s[6:7], -1
	s_mov_b32 s14, 1
	s_mov_b64 s[6:7], 0
	s_andn2_b64 vcc, exec, s[4:5]
	ds_read_b128 v[136:139], v133
	ds_read_b128 v[140:143], v133 offset:16
	s_waitcnt vmcnt(13) lgkmcnt(1)
	v_pk_add_f32 v[188:189], v[136:137], v[188:189]
	v_pk_add_f32 v[190:191], v[138:139], v[190:191]
	global_store_dwordx4 v[130:131], v[188:191], off
	s_waitcnt vmcnt(13) lgkmcnt(0)
	v_pk_add_f32 v[196:197], v[140:141], v[196:197]
	v_pk_add_f32 v[198:199], v[142:143], v[198:199]
	global_store_dwordx4 v[130:131], v[196:199], off offset:16
	global_load_dwordx4 v[188:191], v[130:131], off offset:224
	ds_read_b128 v[136:139], v133 offset:32
	ds_read_b128 v[140:143], v133 offset:48
	s_waitcnt vmcnt(14) lgkmcnt(1)
	v_pk_add_f32 v[204:205], v[136:137], v[204:205]
	v_pk_add_f32 v[206:207], v[138:139], v[206:207]
	global_store_dwordx4 v[130:131], v[204:207], off offset:32
	global_load_dwordx4 v[196:199], v[130:131], off offset:240
	s_waitcnt vmcnt(15) lgkmcnt(0)
	v_pk_add_f32 v[212:213], v[140:141], v[212:213]
	v_pk_add_f32 v[214:215], v[142:143], v[214:215]
	global_store_dwordx4 v[130:131], v[212:215], off offset:48
	ds_read_b128 v[136:139], v133 offset:64
	ds_read_b128 v[140:143], v133 offset:80
	s_waitcnt vmcnt(15) lgkmcnt(1)
	v_pk_add_f32 v[220:221], v[136:137], v[220:221]
	v_pk_add_f32 v[222:223], v[138:139], v[222:223]
	global_store_dwordx4 v[130:131], v[220:223], off offset:64
	s_waitcnt vmcnt(15) lgkmcnt(0)
	v_pk_add_f32 v[228:229], v[140:141], v[228:229]
	v_pk_add_f32 v[230:231], v[142:143], v[230:231]
	global_store_dwordx4 v[130:131], v[228:231], off offset:80
	ds_read_b128 v[136:139], v133 offset:96
	ds_read_b128 v[140:143], v133 offset:112
	s_waitcnt vmcnt(15) lgkmcnt(1)
	v_pk_add_f32 v[192:193], v[136:137], v[192:193]
	v_pk_add_f32 v[194:195], v[138:139], v[194:195]
	global_store_dwordx4 v[130:131], v[192:195], off offset:96
	s_waitcnt vmcnt(15) lgkmcnt(0)
	v_pk_add_f32 v[200:201], v[140:141], v[200:201]
	v_pk_add_f32 v[202:203], v[142:143], v[202:203]
	global_store_dwordx4 v[130:131], v[200:203], off offset:112
	ds_read_b128 v[136:139], v133 offset:128
	ds_read_b128 v[140:143], v133 offset:144
	s_waitcnt vmcnt(15) lgkmcnt(1)
	v_pk_add_f32 v[208:209], v[136:137], v[208:209]
	v_pk_add_f32 v[210:211], v[138:139], v[210:211]
	global_store_dwordx4 v[130:131], v[208:211], off offset:128
	s_waitcnt vmcnt(15) lgkmcnt(0)
	v_pk_add_f32 v[216:217], v[140:141], v[216:217]
	v_pk_add_f32 v[218:219], v[142:143], v[218:219]
	global_store_dwordx4 v[130:131], v[216:219], off offset:144
	ds_read_b128 v[136:139], v133 offset:160
	ds_read_b128 v[140:143], v133 offset:176
	s_waitcnt vmcnt(15) lgkmcnt(1)
	v_pk_add_f32 v[224:225], v[136:137], v[224:225]
	v_pk_add_f32 v[226:227], v[138:139], v[226:227]
	global_store_dwordx4 v[130:131], v[224:227], off offset:160
	s_waitcnt vmcnt(15) lgkmcnt(0)
	v_pk_add_f32 v[232:233], v[140:141], v[232:233]
	v_pk_add_f32 v[234:235], v[142:143], v[234:235]
	global_store_dwordx4 v[130:131], v[232:235], off offset:176
	ds_read_b128 v[136:139], v133 offset:192
	ds_read_b128 v[140:143], v133 offset:208
	s_waitcnt vmcnt(15) lgkmcnt(1)
	v_pk_add_f32 v[144:145], v[136:137], v[144:145]
	v_pk_add_f32 v[146:147], v[138:139], v[146:147]
	global_store_dwordx4 v[130:131], v[144:147], off offset:192
	s_waitcnt vmcnt(15) lgkmcnt(0)
	v_pk_add_f32 v[148:149], v[140:141], v[148:149]
	v_pk_add_f32 v[150:151], v[142:143], v[150:151]
	global_store_dwordx4 v[130:131], v[148:151], off offset:208
	ds_read_b128 v[136:139], v133 offset:224
	ds_read_b128 v[140:143], v133 offset:240
	s_waitcnt vmcnt(13) lgkmcnt(1)
	v_pk_add_f32 v[188:189], v[136:137], v[188:189]
	v_pk_add_f32 v[190:191], v[138:139], v[190:191]
	global_store_dwordx4 v[130:131], v[188:191], off offset:224
	s_waitcnt vmcnt(12) lgkmcnt(0)
	v_pk_add_f32 v[196:197], v[140:141], v[196:197]
	v_pk_add_f32 v[198:199], v[142:143], v[198:199]
	global_store_dwordx4 v[130:131], v[196:199], off offset:240
	s_cbranch_vccz .LBB0_999
